# gu context-row tiles 64x128: 3-slot BK=64 LDS ring (full 128B-line DMA pieces, prefetch distance 2) replacing compiled 2-slot loop
# speedup vs baseline: 1.0080x; 1.0080x over previous
; #define TIDX opaque_tid()
; template <int AI, int BI>
; DI void gemm_stage(const u16* __restrict__ A, int lda, const u16* __restrict__ B, int ldb, char* buf, int tid) {
; #pragma unroll
;   for (int i = 0; i < 2 * AI; ++i) {
;     const int S = tid + NTHR * i, row = S >> 3, c = (S & 7) ^ ((row >> 1) & 7);
;     __builtin_amdgcn_global_load_lds((const unsigned*)(A + (size_t)row * lda + c * 8), (__attribute__((address_space(3))) unsigned*)(buf + S * 16), 16, 0, 0);
;   }
; #pragma unroll
;   for (int i = 0; i < 2 * BI; ++i) {
;     const int S = tid + NTHR * i, row = S >> 3, c = (S & 7) ^ ((row >> 1) & 7);
;     __builtin_amdgcn_global_load_lds((const unsigned*)(B + (size_t)row * ldb + c * 8), (__attribute__((address_space(3))) unsigned*)(buf + 16384 + S * 16), 16, 0, 0);
;   }
; }
; template <int AI, int BI>
; DI void gemm_tile(const u16* __restrict__ A, int lda, const u16* __restrict__ B, int ldb, int nk, bool swap,
;                   f32x16 (&acc)[AI][BI], char* lds) {
;   const int tid = TIDX, lane = tid & 63, wid = tid >> 6;
;   gemm_stage<AI, BI>(A, lda, B, ldb, lds, tid);
;   asm volatile("s_waitcnt vmcnt(0)" ::: "memory");
;   __syncthreads();
;   const int wa = wid >> 1, wb = wid & 1, r = lane & 31, h = lane >> 5, sw = (r >> 1) & 7;
;   const int offA = (swap ? 16384 : 0) + (wa * 32 * AI + r) * 128;
.LBB0_421:
	v_readlane_b32 s6, v244, 50
	v_readlane_b32 s7, v244, 51
	s_andn2_b64 vcc, exec, s[6:7]
	s_mov_b32 s49, 0x1ffffe0
	s_cbranch_vccnz .LBB0_425
	s_add_u32 s10, s8, 0x77b7000
	s_addc_u32 s11, s9, 0
	s_add_u32 s12, s8, 0x1c4b7000
	s_addc_u32 s13, s9, 0
	s_add_u32 s6, s8, 0x9bb7000
	s_addc_u32 s7, s9, 0
	v_readlane_b32 s14, v243, 18
	v_readlane_b32 s15, v243, 10
	v_readlane_b32 s16, v243, 8
	v_readlane_b32 s48, v243, 7
	s_mov_b64 s[50:51], 0x200
	s_mov_b64 s[52:53], 0x80
	s_mov_b64 s[54:55], 0x180
	s_mov_b64 s[64:65], 0x300
	s_mov_b64 s[66:67], 0x380
	s_mov_b64 s[68:69], 0x400
	s_mov_b64 s[70:71], 0x480
	s_mov_b64 s[72:73], 0x500
	s_mov_b64 s[74:75], 0x580
	s_mov_b64 s[76:77], 0x600
	s_mov_b64 s[56:57], 0x280
	s_cmpk_lg_u32 s92, 0x200
	s_cbranch_scc1 .LBB0_423
	v_and_b32_e32 v95, 31, v178
	v_bfe_u32 v96, v178, 5, 1
	v_bfe_u32 v97, v178, 1, 3
	v_bfe_u32 v98, v178, 7, 1
	v_lshl_add_u32 v98, v98, 5, v95
	v_lshlrev_b32_e32 v98, 7, v98
	v_add_u32_e32 v98, 0xc000, v98
	v_bfe_u32 v99, v178, 6, 1
	v_lshl_add_u32 v99, v99, 6, v95
	v_lshlrev_b32_e32 v99, 7, v99
	v_mov_b32_e32 v0, v96
	v_xor_b32_e32 v0, v0, v97
	v_lshlrev_b32_e32 v0, 4, v0
	v_add_u32_e32 v82, v98, v0
	v_add_u32_e32 v86, v99, v0
	v_add_u32_e32 v0, 2, v96
	v_xor_b32_e32 v0, v0, v97
	v_lshlrev_b32_e32 v0, 4, v0
	v_add_u32_e32 v83, v98, v0
	v_add_u32_e32 v87, v99, v0
	v_add_u32_e32 v0, 4, v96
	v_xor_b32_e32 v0, v0, v97
	v_lshlrev_b32_e32 v0, 4, v0
	v_add_u32_e32 v84, v98, v0
	v_add_u32_e32 v88, v99, v0
	v_add_u32_e32 v0, 6, v96
	v_xor_b32_e32 v0, v0, v97
	v_lshlrev_b32_e32 v0, 4, v0
	v_add_u32_e32 v85, v98, v0
	v_add_u32_e32 v89, v99, v0
	v_bfe_u32 v96, v178, 7, 1
	v_lshlrev_b32_e32 v96, 5, v96
	v_bfe_u32 v97, v178, 5, 1
	v_lshl_add_u32 v96, v97, 2, v96
	v_mul_u32_u24_e32 v96, 0xb00, v96
	v_bfe_u32 v97, v178, 6, 1
	v_lshl_add_u32 v97, v97, 5, v95
	v_add_u32_e32 v96, v96, v97
	v_lshlrev_b32_e32 v94, 1, v96
	v_lshrrev_b32_e32 v95, 3, v178
	v_and_b32_e32 v96, 7, v178
	v_bfe_u32 v97, v178, 4, 3
	v_xor_b32_e32 v96, v96, v97
	v_lshlrev_b32_e32 v96, 4, v96
	v_lshl_add_u32 v90, v95, 11, v96
	v_add_u32_e32 v91, 0x10000, v90
	v_add_u32_e32 v92, 0x20000, v90
	v_add_u32_e32 v93, 0x30000, v90
	v_lshrrev_b32_e32 v95, 6, v178
	s_nop 1
	v_readfirstlane_b32 s17, v95
	s_lshl_b32 s17, s17, 10
	s_mov_b32 s36, s14
.Lgc1_tile:
	s_mul_i32 s37, s36, 0xba2f
	s_lshr_b32 s37, s37, 24
	s_mul_i32 s40, s37, 0x160
	s_sub_u32 s40, s36, s40
	s_lshr_b32 s41, s40, 3
	s_and_b32 s40, s40, 7
	s_lshl_b32 s37, s37, 3
	s_or_b32 s37, s37, s40
	s_lshl_b32 s37, s37, 6
	s_bitset1_b32 s37, 14
	s_lshl_b32 s46, s37, 11
	s_add_u32 s8, s10, s46
	s_addc_u32 s9, s11, 0
	s_lshl_b32 s46, s41, 18
	s_add_u32 s28, s12, s46
	s_addc_u32 s29, s13, 0
	s_mul_i32 s46, s37, 0x1600
	s_lshl_b32 s47, s41, 7
	s_add_u32 s46, s46, s47
	s_add_u32 s34, s6, s46
	s_addc_u32 s35, s7, 0
	s_barrier
	v_mov_b32_e32 v2, 0
	v_mov_b32_e32 v3, 0
	v_mov_b32_e32 v4, 0
	v_mov_b32_e32 v5, 0
	v_mov_b32_e32 v6, 0
	v_mov_b32_e32 v7, 0
	v_mov_b32_e32 v8, 0
	v_mov_b32_e32 v9, 0
	v_mov_b32_e32 v10, 0
	v_mov_b32_e32 v11, 0
	v_mov_b32_e32 v12, 0
	v_mov_b32_e32 v13, 0
	v_mov_b32_e32 v14, 0
	v_mov_b32_e32 v15, 0
	v_mov_b32_e32 v16, 0
	v_mov_b32_e32 v17, 0
	v_mov_b32_e32 v18, 0
	v_mov_b32_e32 v19, 0
	v_mov_b32_e32 v20, 0
	v_mov_b32_e32 v21, 0
	v_mov_b32_e32 v22, 0
	v_mov_b32_e32 v23, 0
	v_mov_b32_e32 v24, 0
	v_mov_b32_e32 v25, 0
	v_mov_b32_e32 v26, 0
	v_mov_b32_e32 v27, 0
	v_mov_b32_e32 v28, 0
	v_mov_b32_e32 v29, 0
	v_mov_b32_e32 v30, 0
	v_mov_b32_e32 v31, 0
	v_mov_b32_e32 v32, 0
	v_mov_b32_e32 v33, 0
	s_add_u32 m0, s17, 49152
	s_nop 0
	global_load_lds_dwordx4 v90, s[8:9]
	s_add_u32 m0, s17, 53248
	s_nop 0
	global_load_lds_dwordx4 v91, s[8:9]
	s_add_u32 m0, s17, 0
	s_nop 0
	global_load_lds_dwordx4 v90, s[28:29]
	s_add_u32 m0, s17, 4096
	s_nop 0
	global_load_lds_dwordx4 v91, s[28:29]
	s_add_u32 m0, s17, 8192
	s_nop 0
	global_load_lds_dwordx4 v92, s[28:29]
	s_add_u32 m0, s17, 12288
	s_nop 0
	global_load_lds_dwordx4 v93, s[28:29]
	s_add_u32 s8, s8, 0x80
	s_addc_u32 s9, s9, 0
	s_add_u32 s28, s28, 0x80
	s_addc_u32 s29, s29, 0
	s_add_u32 m0, s17, 57344
	s_nop 0
	global_load_lds_dwordx4 v90, s[8:9]
	s_add_u32 m0, s17, 61440
	s_nop 0
	global_load_lds_dwordx4 v91, s[8:9]
	s_add_u32 m0, s17, 16384
	s_nop 0
	global_load_lds_dwordx4 v90, s[28:29]
	s_add_u32 m0, s17, 20480
	s_nop 0
	global_load_lds_dwordx4 v91, s[28:29]
	s_add_u32 m0, s17, 24576
	s_nop 0
	global_load_lds_dwordx4 v92, s[28:29]
	s_add_u32 m0, s17, 28672
	s_nop 0
	global_load_lds_dwordx4 v93, s[28:29]
	s_add_u32 s8, s8, 0x80
	s_addc_u32 s9, s9, 0
	s_add_u32 s28, s28, 0x80
	s_addc_u32 s29, s29, 0
	s_mov_b32 s18, 4
; #define MFMA(a, b, c) __builtin_amdgcn_mfma_f32_32x32x16_bf16((a), (b), (c), 0, 0, 0)
; template <int AI, int BI>
; DI void gemm_tile(const u16* __restrict__ A, int lda, const u16* __restrict__ B, int ldb, int nk, bool swap,
;                   f32x16 (&acc)[AI][BI], char* lds) {
;     ...
;   for (int kt = 0; kt < nk; ++kt) {
;     const char* cur = lds + (kt & 1) * 32768;
;     if (kt + 1 < nk) gemm_stage<AI, BI>(A + (kt + 1) * 64, lda, B + (kt + 1) * 64, ldb, lds + ((kt + 1) & 1) * 32768, tid);
; #pragma unroll
;     for (int ks = 0; ks < 4; ++ks) {
;       const int co = ((ks * 2 + h) ^ sw) << 4;
;       s16x8 fa[AI], fb[BI];
; #pragma unroll
;       for (int i = 0; i < AI; ++i) fa[i] = *(const s16x8*)(cur + offA + i * 4096 + co);
; #pragma unroll
;       for (int i = 0; i < BI; ++i) fb[i] = *(const s16x8*)(cur + offB + i * 4096 + co);
; #pragma unroll
;       for (int i = 0; i < AI; ++i)
; #pragma unroll
;         for (int j = 0; j < BI; ++j) acc[i][j] = MFMA(fa[i], fb[j], acc[i][j]);
;     }
;     asm volatile("s_waitcnt vmcnt(0)" ::: "memory");
;     __syncthreads();
;   }
.Lgc1_kloop:
	s_waitcnt vmcnt(6)
	s_barrier
	s_add_u32 m0, s17, 65664
	s_nop 0
	global_load_lds_dwordx4 v90, s[8:9]
	s_add_u32 m0, s17, 69760
	s_nop 0
	global_load_lds_dwordx4 v91, s[8:9]
	s_add_u32 m0, s17, 32768
	s_nop 0
	global_load_lds_dwordx4 v90, s[28:29]
	s_add_u32 m0, s17, 36864
	s_nop 0
	global_load_lds_dwordx4 v91, s[28:29]
	s_add_u32 m0, s17, 40960
	s_nop 0
	global_load_lds_dwordx4 v92, s[28:29]
	s_add_u32 m0, s17, 45056
	s_nop 0
	global_load_lds_dwordx4 v93, s[28:29]
	s_add_u32 s8, s8, 0x80
	s_addc_u32 s9, s9, 0
	s_add_u32 s28, s28, 0x80
	s_addc_u32 s29, s29, 0
	ds_read_b128 v[34:37], v82 offset:0
	ds_read_b128 v[38:41], v86 offset:0
	ds_read_b128 v[42:45], v86 offset:4096
	ds_read_b128 v[46:49], v83 offset:0
	ds_read_b128 v[50:53], v87 offset:0
	ds_read_b128 v[54:57], v87 offset:4096
	ds_read_b128 v[58:61], v84 offset:0
	ds_read_b128 v[62:65], v88 offset:0
	ds_read_b128 v[66:69], v88 offset:4096
	ds_read_b128 v[70:73], v85 offset:0
	ds_read_b128 v[74:77], v89 offset:0
	ds_read_b128 v[78:81], v89 offset:4096
	s_waitcnt lgkmcnt(10)
	v_mfma_f32_32x32x16_bf16 v[2:17], v[34:37], v[38:41], v[2:17]
	s_waitcnt lgkmcnt(9)
	v_mfma_f32_32x32x16_bf16 v[18:33], v[34:37], v[42:45], v[18:33]
	s_waitcnt lgkmcnt(7)
	v_mfma_f32_32x32x16_bf16 v[2:17], v[46:49], v[50:53], v[2:17]
	s_waitcnt lgkmcnt(6)
	v_mfma_f32_32x32x16_bf16 v[18:33], v[46:49], v[54:57], v[18:33]
	s_waitcnt lgkmcnt(4)
	v_mfma_f32_32x32x16_bf16 v[2:17], v[58:61], v[62:65], v[2:17]
	s_waitcnt lgkmcnt(3)
	v_mfma_f32_32x32x16_bf16 v[18:33], v[58:61], v[66:69], v[18:33]
	s_waitcnt lgkmcnt(1)
	v_mfma_f32_32x32x16_bf16 v[2:17], v[70:73], v[74:77], v[2:17]
	s_waitcnt lgkmcnt(0)
	v_mfma_f32_32x32x16_bf16 v[18:33], v[70:73], v[78:81], v[18:33]
	s_waitcnt vmcnt(6)
	s_barrier
	s_add_u32 m0, s17, 49152
	s_nop 0
	global_load_lds_dwordx4 v90, s[8:9]
	s_add_u32 m0, s17, 53248
	s_nop 0
	global_load_lds_dwordx4 v91, s[8:9]
	s_add_u32 m0, s17, 0
	s_nop 0
	global_load_lds_dwordx4 v90, s[28:29]
	s_add_u32 m0, s17, 4096
	s_nop 0
	global_load_lds_dwordx4 v91, s[28:29]
	s_add_u32 m0, s17, 8192
	s_nop 0
	global_load_lds_dwordx4 v92, s[28:29]
	s_add_u32 m0, s17, 12288
	s_nop 0
	global_load_lds_dwordx4 v93, s[28:29]
	s_add_u32 s8, s8, 0x80
	s_addc_u32 s9, s9, 0
	s_add_u32 s28, s28, 0x80
	s_addc_u32 s29, s29, 0
	ds_read_b128 v[34:37], v82 offset:8192
	ds_read_b128 v[38:41], v86 offset:16384
	ds_read_b128 v[42:45], v86 offset:20480
	ds_read_b128 v[46:49], v83 offset:8192
	ds_read_b128 v[50:53], v87 offset:16384
	ds_read_b128 v[54:57], v87 offset:20480
	ds_read_b128 v[58:61], v84 offset:8192
	ds_read_b128 v[62:65], v88 offset:16384
	ds_read_b128 v[66:69], v88 offset:20480
	ds_read_b128 v[70:73], v85 offset:8192
	ds_read_b128 v[74:77], v89 offset:16384
	ds_read_b128 v[78:81], v89 offset:20480
	s_waitcnt lgkmcnt(10)
	v_mfma_f32_32x32x16_bf16 v[2:17], v[34:37], v[38:41], v[2:17]
	s_waitcnt lgkmcnt(9)
	v_mfma_f32_32x32x16_bf16 v[18:33], v[34:37], v[42:45], v[18:33]
	s_waitcnt lgkmcnt(7)
	v_mfma_f32_32x32x16_bf16 v[2:17], v[46:49], v[50:53], v[2:17]
	s_waitcnt lgkmcnt(6)
	v_mfma_f32_32x32x16_bf16 v[18:33], v[46:49], v[54:57], v[18:33]
	s_waitcnt lgkmcnt(4)
	v_mfma_f32_32x32x16_bf16 v[2:17], v[58:61], v[62:65], v[2:17]
	s_waitcnt lgkmcnt(3)
	v_mfma_f32_32x32x16_bf16 v[18:33], v[58:61], v[66:69], v[18:33]
	s_waitcnt lgkmcnt(1)
	v_mfma_f32_32x32x16_bf16 v[2:17], v[70:73], v[74:77], v[2:17]
	s_waitcnt lgkmcnt(0)
	v_mfma_f32_32x32x16_bf16 v[18:33], v[70:73], v[78:81], v[18:33]
	s_waitcnt vmcnt(6)
	s_barrier
	s_add_u32 m0, s17, 57344
	s_nop 0
	global_load_lds_dwordx4 v90, s[8:9]
	s_add_u32 m0, s17, 61440
	s_nop 0
	global_load_lds_dwordx4 v91, s[8:9]
	s_add_u32 m0, s17, 16384
	s_nop 0
	global_load_lds_dwordx4 v90, s[28:29]
	s_add_u32 m0, s17, 20480
	s_nop 0
	global_load_lds_dwordx4 v91, s[28:29]
	s_add_u32 m0, s17, 24576
	s_nop 0
	global_load_lds_dwordx4 v92, s[28:29]
	s_add_u32 m0, s17, 28672
	s_nop 0
	global_load_lds_dwordx4 v93, s[28:29]
	s_add_u32 s8, s8, 0x80
	s_addc_u32 s9, s9, 0
	s_add_u32 s28, s28, 0x80
	s_addc_u32 s29, s29, 0
	ds_read_b128 v[34:37], v82 offset:16512
	ds_read_b128 v[38:41], v86 offset:32768
	ds_read_b128 v[42:45], v86 offset:36864
	ds_read_b128 v[46:49], v83 offset:16512
	ds_read_b128 v[50:53], v87 offset:32768
	ds_read_b128 v[54:57], v87 offset:36864
	ds_read_b128 v[58:61], v84 offset:16512
	ds_read_b128 v[62:65], v88 offset:32768
	ds_read_b128 v[66:69], v88 offset:36864
	ds_read_b128 v[70:73], v85 offset:16512
	ds_read_b128 v[74:77], v89 offset:32768
	ds_read_b128 v[78:81], v89 offset:36864
	s_waitcnt lgkmcnt(10)
	v_mfma_f32_32x32x16_bf16 v[2:17], v[34:37], v[38:41], v[2:17]
	s_waitcnt lgkmcnt(9)
	v_mfma_f32_32x32x16_bf16 v[18:33], v[34:37], v[42:45], v[18:33]
	s_waitcnt lgkmcnt(7)
	v_mfma_f32_32x32x16_bf16 v[2:17], v[46:49], v[50:53], v[2:17]
	s_waitcnt lgkmcnt(6)
	v_mfma_f32_32x32x16_bf16 v[18:33], v[46:49], v[54:57], v[18:33]
	s_waitcnt lgkmcnt(4)
	v_mfma_f32_32x32x16_bf16 v[2:17], v[58:61], v[62:65], v[2:17]
	s_waitcnt lgkmcnt(3)
	v_mfma_f32_32x32x16_bf16 v[18:33], v[58:61], v[66:69], v[18:33]
	s_waitcnt lgkmcnt(1)
	v_mfma_f32_32x32x16_bf16 v[2:17], v[70:73], v[74:77], v[2:17]
	s_waitcnt lgkmcnt(0)
	v_mfma_f32_32x32x16_bf16 v[18:33], v[70:73], v[78:81], v[18:33]
	s_sub_u32 s18, s18, 1
	s_cmp_lg_u32 s18, 0
	s_cbranch_scc1 .Lgc1_kloop
	s_waitcnt vmcnt(6)
	s_barrier
; #define MFMA(a, b, c) __builtin_amdgcn_mfma_f32_32x32x16_bf16((a), (b), (c), 0, 0, 0)
; template <int AI, int BI>
; DI void gemm_tile(const u16* __restrict__ A, int lda, const u16* __restrict__ B, int ldb, int nk, bool swap,
;                   f32x16 (&acc)[AI][BI], char* lds) {
;     ...
;   for (int kt = 0; kt < nk; ++kt) {
;     const char* cur = lds + (kt & 1) * 32768;
;     if (kt + 1 < nk) gemm_stage<AI, BI>(A + (kt + 1) * 64, lda, B + (kt + 1) * 64, ldb, lds + ((kt + 1) & 1) * 32768, tid);
; #pragma unroll
;     for (int ks = 0; ks < 4; ++ks) {
;       const int co = ((ks * 2 + h) ^ sw) << 4;
;       s16x8 fa[AI], fb[BI];
; #pragma unroll
;       for (int i = 0; i < AI; ++i) fa[i] = *(const s16x8*)(cur + offA + i * 4096 + co);
; #pragma unroll
;       for (int i = 0; i < BI; ++i) fb[i] = *(const s16x8*)(cur + offB + i * 4096 + co);
; #pragma unroll
;       for (int i = 0; i < AI; ++i)
; #pragma unroll
;         for (int j = 0; j < BI; ++j) acc[i][j] = MFMA(fa[i], fb[j], acc[i][j]);
;     }
;     asm volatile("s_waitcnt vmcnt(0)" ::: "memory");
;     __syncthreads();
;   }
	s_add_u32 m0, s17, 65664
	s_nop 0
	global_load_lds_dwordx4 v90, s[8:9]
	s_add_u32 m0, s17, 69760
	s_nop 0
	global_load_lds_dwordx4 v91, s[8:9]
	s_add_u32 m0, s17, 32768
	s_nop 0
	global_load_lds_dwordx4 v90, s[28:29]
	s_add_u32 m0, s17, 36864
	s_nop 0
	global_load_lds_dwordx4 v91, s[28:29]
	s_add_u32 m0, s17, 40960
	s_nop 0
	global_load_lds_dwordx4 v92, s[28:29]
	s_add_u32 m0, s17, 45056
	s_nop 0
	global_load_lds_dwordx4 v93, s[28:29]
	s_add_u32 s8, s8, 0x80
	s_addc_u32 s9, s9, 0
	s_add_u32 s28, s28, 0x80
	s_addc_u32 s29, s29, 0
	ds_read_b128 v[34:37], v82 offset:0
	ds_read_b128 v[38:41], v86 offset:0
	ds_read_b128 v[42:45], v86 offset:4096
	ds_read_b128 v[46:49], v83 offset:0
	ds_read_b128 v[50:53], v87 offset:0
	ds_read_b128 v[54:57], v87 offset:4096
	ds_read_b128 v[58:61], v84 offset:0
	ds_read_b128 v[62:65], v88 offset:0
	ds_read_b128 v[66:69], v88 offset:4096
	ds_read_b128 v[70:73], v85 offset:0
	ds_read_b128 v[74:77], v89 offset:0
	ds_read_b128 v[78:81], v89 offset:4096
	s_waitcnt lgkmcnt(10)
	v_mfma_f32_32x32x16_bf16 v[2:17], v[34:37], v[38:41], v[2:17]
	s_waitcnt lgkmcnt(9)
	v_mfma_f32_32x32x16_bf16 v[18:33], v[34:37], v[42:45], v[18:33]
	s_waitcnt lgkmcnt(7)
	v_mfma_f32_32x32x16_bf16 v[2:17], v[46:49], v[50:53], v[2:17]
	s_waitcnt lgkmcnt(6)
	v_mfma_f32_32x32x16_bf16 v[18:33], v[46:49], v[54:57], v[18:33]
	s_waitcnt lgkmcnt(4)
	v_mfma_f32_32x32x16_bf16 v[2:17], v[58:61], v[62:65], v[2:17]
	s_waitcnt lgkmcnt(3)
	v_mfma_f32_32x32x16_bf16 v[18:33], v[58:61], v[66:69], v[18:33]
	s_waitcnt lgkmcnt(1)
	v_mfma_f32_32x32x16_bf16 v[2:17], v[70:73], v[74:77], v[2:17]
	s_waitcnt lgkmcnt(0)
	v_mfma_f32_32x32x16_bf16 v[18:33], v[70:73], v[78:81], v[18:33]
	s_waitcnt vmcnt(6)
	s_barrier
	s_add_u32 m0, s17, 49152
	s_nop 0
	global_load_lds_dwordx4 v90, s[8:9]
	s_add_u32 m0, s17, 53248
	s_nop 0
	global_load_lds_dwordx4 v91, s[8:9]
	s_add_u32 m0, s17, 0
	s_nop 0
	global_load_lds_dwordx4 v90, s[28:29]
	s_add_u32 m0, s17, 4096
	s_nop 0
	global_load_lds_dwordx4 v91, s[28:29]
	s_add_u32 m0, s17, 8192
	s_nop 0
	global_load_lds_dwordx4 v92, s[28:29]
	s_add_u32 m0, s17, 12288
	s_nop 0
	global_load_lds_dwordx4 v93, s[28:29]
	s_add_u32 s8, s8, 0x80
	s_addc_u32 s9, s9, 0
	s_add_u32 s28, s28, 0x80
	s_addc_u32 s29, s29, 0
	ds_read_b128 v[34:37], v82 offset:8192
	ds_read_b128 v[38:41], v86 offset:16384
	ds_read_b128 v[42:45], v86 offset:20480
	ds_read_b128 v[46:49], v83 offset:8192
	ds_read_b128 v[50:53], v87 offset:16384
	ds_read_b128 v[54:57], v87 offset:20480
	ds_read_b128 v[58:61], v84 offset:8192
	ds_read_b128 v[62:65], v88 offset:16384
	ds_read_b128 v[66:69], v88 offset:20480
	ds_read_b128 v[70:73], v85 offset:8192
	ds_read_b128 v[74:77], v89 offset:16384
	ds_read_b128 v[78:81], v89 offset:20480
	s_waitcnt lgkmcnt(10)
	v_mfma_f32_32x32x16_bf16 v[2:17], v[34:37], v[38:41], v[2:17]
	s_waitcnt lgkmcnt(9)
	v_mfma_f32_32x32x16_bf16 v[18:33], v[34:37], v[42:45], v[18:33]
	s_waitcnt lgkmcnt(7)
	v_mfma_f32_32x32x16_bf16 v[2:17], v[46:49], v[50:53], v[2:17]
	s_waitcnt lgkmcnt(6)
	v_mfma_f32_32x32x16_bf16 v[18:33], v[46:49], v[54:57], v[18:33]
	s_waitcnt lgkmcnt(4)
	v_mfma_f32_32x32x16_bf16 v[2:17], v[58:61], v[62:65], v[2:17]
	s_waitcnt lgkmcnt(3)
	v_mfma_f32_32x32x16_bf16 v[18:33], v[58:61], v[66:69], v[18:33]
	s_waitcnt lgkmcnt(1)
	v_mfma_f32_32x32x16_bf16 v[2:17], v[70:73], v[74:77], v[2:17]
	s_waitcnt lgkmcnt(0)
	v_mfma_f32_32x32x16_bf16 v[18:33], v[70:73], v[78:81], v[18:33]
	s_waitcnt vmcnt(6)
	s_barrier
	ds_read_b128 v[34:37], v82 offset:16512
	ds_read_b128 v[38:41], v86 offset:32768
	ds_read_b128 v[42:45], v86 offset:36864
	ds_read_b128 v[46:49], v83 offset:16512
	ds_read_b128 v[50:53], v87 offset:32768
	ds_read_b128 v[54:57], v87 offset:36864
	ds_read_b128 v[58:61], v84 offset:16512
	ds_read_b128 v[62:65], v88 offset:32768
	ds_read_b128 v[66:69], v88 offset:36864
	ds_read_b128 v[70:73], v85 offset:16512
	ds_read_b128 v[74:77], v89 offset:32768
	ds_read_b128 v[78:81], v89 offset:36864
	s_waitcnt lgkmcnt(10)
	v_mfma_f32_32x32x16_bf16 v[2:17], v[34:37], v[38:41], v[2:17]
	s_waitcnt lgkmcnt(9)
	v_mfma_f32_32x32x16_bf16 v[18:33], v[34:37], v[42:45], v[18:33]
	s_waitcnt lgkmcnt(7)
	v_mfma_f32_32x32x16_bf16 v[2:17], v[46:49], v[50:53], v[2:17]
	s_waitcnt lgkmcnt(6)
	v_mfma_f32_32x32x16_bf16 v[18:33], v[46:49], v[54:57], v[18:33]
	s_waitcnt lgkmcnt(4)
	v_mfma_f32_32x32x16_bf16 v[2:17], v[58:61], v[62:65], v[2:17]
	s_waitcnt lgkmcnt(3)
	v_mfma_f32_32x32x16_bf16 v[18:33], v[58:61], v[66:69], v[18:33]
	s_waitcnt lgkmcnt(1)
	v_mfma_f32_32x32x16_bf16 v[2:17], v[70:73], v[74:77], v[2:17]
	s_waitcnt lgkmcnt(0)
	v_mfma_f32_32x32x16_bf16 v[18:33], v[70:73], v[78:81], v[18:33]
	s_waitcnt vmcnt(0)
	s_barrier
; #define MFMA(a, b, c) __builtin_amdgcn_mfma_f32_32x32x16_bf16((a), (b), (c), 0, 0, 0)
; #define GAS __attribute__((address_space(1)))
; DI int opaque0() { int z = 0; asm volatile("" : "+v"(z)); return z; }
; template <int AI, int BI>
; DI void gemm_tile(const u16* __restrict__ A, int lda, const u16* __restrict__ B, int ldb, int nk, bool swap,
;                   f32x16 (&acc)[AI][BI], char* lds) {
;     ...
;       for (int i = 0; i < AI; ++i) fa[i] = *(const s16x8*)(cur + offA + i * 4096 + co);
; #pragma unroll
;       for (int i = 0; i < BI; ++i) fb[i] = *(const s16x8*)(cur + offB + i * 4096 + co);
; #pragma unroll
;       for (int i = 0; i < AI; ++i)
; #pragma unroll
;         for (int j = 0; j < BI; ++j) acc[i][j] = MFMA(fa[i], fb[j], acc[i][j]);
; template <int AI>
; DI void gu_tile(char* wsb, int sub, int m0, int n0, char* lds) {
;     ...
;   const int m0e = m0 + opaque0();
;   const int hc = (n0 >> 1) + wb * 32 + r;
;   GAS u16* HIDu = uptr(HID);
;   const unsigned ib = (unsigned)((m0e + wa * 32 * AI + 4 * h) * 2816 + hc);
; #pragma unroll
;   for (int ai = 0; ai < AI; ++ai)
; #pragma unroll
;     for (int reg = 0; reg < 16; ++reg) {
;       float g = acc[ai][0][reg], u = acc[ai][1][reg];
;       float v = g * __builtin_amdgcn_rcpf(1.f + __expf(-g)) * u;
;       HIDu[ib + (unsigned)((ai * 32 + (reg & 3) + 8 * (reg >> 2)) * 2816)] = f2bf(v);
;       if ((reg & 7) == 7) __builtin_amdgcn_sched_barrier(0);
;     }
	ds_read_b128 v[34:37], v82 offset:0
	ds_read_b128 v[38:41], v86 offset:0
	ds_read_b128 v[42:45], v86 offset:4096
	ds_read_b128 v[46:49], v83 offset:0
	ds_read_b128 v[50:53], v87 offset:0
	ds_read_b128 v[54:57], v87 offset:4096
	ds_read_b128 v[58:61], v84 offset:0
	ds_read_b128 v[62:65], v88 offset:0
	ds_read_b128 v[66:69], v88 offset:4096
	ds_read_b128 v[70:73], v85 offset:0
	ds_read_b128 v[74:77], v89 offset:0
	ds_read_b128 v[78:81], v89 offset:4096
	s_waitcnt lgkmcnt(10)
	v_mfma_f32_32x32x16_bf16 v[2:17], v[34:37], v[38:41], v[2:17]
	s_waitcnt lgkmcnt(9)
	v_mfma_f32_32x32x16_bf16 v[18:33], v[34:37], v[42:45], v[18:33]
	s_waitcnt lgkmcnt(7)
	v_mfma_f32_32x32x16_bf16 v[2:17], v[46:49], v[50:53], v[2:17]
	s_waitcnt lgkmcnt(6)
	v_mfma_f32_32x32x16_bf16 v[18:33], v[46:49], v[54:57], v[18:33]
	s_waitcnt lgkmcnt(4)
	v_mfma_f32_32x32x16_bf16 v[2:17], v[58:61], v[62:65], v[2:17]
	s_waitcnt lgkmcnt(3)
	v_mfma_f32_32x32x16_bf16 v[18:33], v[58:61], v[66:69], v[18:33]
	s_waitcnt lgkmcnt(1)
	v_mfma_f32_32x32x16_bf16 v[2:17], v[70:73], v[74:77], v[2:17]
	s_waitcnt lgkmcnt(0)
	v_mfma_f32_32x32x16_bf16 v[18:33], v[70:73], v[78:81], v[18:33]
	s_nop 7
	s_nop 7
	v_mul_f32_e32 v66, 0xbfb8aa3b, v2
	v_mul_f32_e32 v68, 0xbfb8aa3b, v3
	v_exp_f32_e32 v66, v66
	v_exp_f32_e32 v68, v68
	v_add_u32_e32 v67, 0x0, v94
	v_add_f32_e32 v66, 1.0, v66
	v_add_f32_e32 v68, 1.0, v68
	v_rcp_f32_e32 v66, v66
	v_rcp_f32_e32 v68, v68
	v_add_u32_e32 v69, 0x1600, v94
	v_mul_f32_e32 v66, v2, v66
	v_mul_f32_e32 v68, v3, v68
	v_mul_f32_e32 v66, v18, v66
	v_mul_f32_e32 v68, v19, v68
	v_cvt_pk_bf16_f32 v66, v66, v66
	v_cvt_pk_bf16_f32 v68, v68, v68
	global_store_short v67, v66, s[34:35]
	global_store_short v69, v68, s[34:35]
	v_mul_f32_e32 v66, 0xbfb8aa3b, v4
	v_mul_f32_e32 v68, 0xbfb8aa3b, v5
	v_exp_f32_e32 v66, v66
	v_exp_f32_e32 v68, v68
	v_add_u32_e32 v67, 0x2c00, v94
	v_add_f32_e32 v66, 1.0, v66
	v_add_f32_e32 v68, 1.0, v68
	v_rcp_f32_e32 v66, v66
	v_rcp_f32_e32 v68, v68
	v_add_u32_e32 v69, 0x4200, v94
	v_mul_f32_e32 v66, v4, v66
	v_mul_f32_e32 v68, v5, v68
	v_mul_f32_e32 v66, v20, v66
	v_mul_f32_e32 v68, v21, v68
	v_cvt_pk_bf16_f32 v66, v66, v66
	v_cvt_pk_bf16_f32 v68, v68, v68
	global_store_short v67, v66, s[34:35]
	global_store_short v69, v68, s[34:35]
	v_mul_f32_e32 v66, 0xbfb8aa3b, v6
	v_mul_f32_e32 v68, 0xbfb8aa3b, v7
	v_exp_f32_e32 v66, v66
	v_exp_f32_e32 v68, v68
	v_add_u32_e32 v67, 0xb000, v94
	v_add_f32_e32 v66, 1.0, v66
	v_add_f32_e32 v68, 1.0, v68
	v_rcp_f32_e32 v66, v66
	v_rcp_f32_e32 v68, v68
	v_add_u32_e32 v69, 0xc600, v94
	v_mul_f32_e32 v66, v6, v66
	v_mul_f32_e32 v68, v7, v68
	v_mul_f32_e32 v66, v22, v66
	v_mul_f32_e32 v68, v23, v68
	v_cvt_pk_bf16_f32 v66, v66, v66
	v_cvt_pk_bf16_f32 v68, v68, v68
	global_store_short v67, v66, s[34:35]
	global_store_short v69, v68, s[34:35]
	v_mul_f32_e32 v66, 0xbfb8aa3b, v8
	v_mul_f32_e32 v68, 0xbfb8aa3b, v9
	v_exp_f32_e32 v66, v66
	v_exp_f32_e32 v68, v68
	v_add_u32_e32 v67, 0xdc00, v94
	v_add_f32_e32 v66, 1.0, v66
	v_add_f32_e32 v68, 1.0, v68
	v_rcp_f32_e32 v66, v66
	v_rcp_f32_e32 v68, v68
	v_add_u32_e32 v69, 0xf200, v94
	v_mul_f32_e32 v66, v8, v66
	v_mul_f32_e32 v68, v9, v68
	v_mul_f32_e32 v66, v24, v66
	v_mul_f32_e32 v68, v25, v68
	v_cvt_pk_bf16_f32 v66, v66, v66
	v_cvt_pk_bf16_f32 v68, v68, v68
	global_store_short v67, v66, s[34:35]
	global_store_short v69, v68, s[34:35]
	v_mul_f32_e32 v66, 0xbfb8aa3b, v10
	v_mul_f32_e32 v68, 0xbfb8aa3b, v11
	v_exp_f32_e32 v66, v66
	v_exp_f32_e32 v68, v68
	v_add_u32_e32 v67, 0x16000, v94
	v_add_f32_e32 v66, 1.0, v66
	v_add_f32_e32 v68, 1.0, v68
	v_rcp_f32_e32 v66, v66
	v_rcp_f32_e32 v68, v68
	v_add_u32_e32 v69, 0x17600, v94
	v_mul_f32_e32 v66, v10, v66
	v_mul_f32_e32 v68, v11, v68
	v_mul_f32_e32 v66, v26, v66
	v_mul_f32_e32 v68, v27, v68
	v_cvt_pk_bf16_f32 v66, v66, v66
	v_cvt_pk_bf16_f32 v68, v68, v68
	global_store_short v67, v66, s[34:35]
	global_store_short v69, v68, s[34:35]
	v_mul_f32_e32 v66, 0xbfb8aa3b, v12
	v_mul_f32_e32 v68, 0xbfb8aa3b, v13
	v_exp_f32_e32 v66, v66
	v_exp_f32_e32 v68, v68
	v_add_u32_e32 v67, 0x18c00, v94
	v_add_f32_e32 v66, 1.0, v66
	v_add_f32_e32 v68, 1.0, v68
	v_rcp_f32_e32 v66, v66
	v_rcp_f32_e32 v68, v68
	v_add_u32_e32 v69, 0x1a200, v94
	v_mul_f32_e32 v66, v12, v66
	v_mul_f32_e32 v68, v13, v68
	v_mul_f32_e32 v66, v28, v66
	v_mul_f32_e32 v68, v29, v68
	v_cvt_pk_bf16_f32 v66, v66, v66
	v_cvt_pk_bf16_f32 v68, v68, v68
	global_store_short v67, v66, s[34:35]
	global_store_short v69, v68, s[34:35]
	v_mul_f32_e32 v66, 0xbfb8aa3b, v14
	v_mul_f32_e32 v68, 0xbfb8aa3b, v15
	v_exp_f32_e32 v66, v66
	v_exp_f32_e32 v68, v68
	v_add_u32_e32 v67, 0x21000, v94
	v_add_f32_e32 v66, 1.0, v66
	v_add_f32_e32 v68, 1.0, v68
	v_rcp_f32_e32 v66, v66
	v_rcp_f32_e32 v68, v68
	v_add_u32_e32 v69, 0x22600, v94
	v_mul_f32_e32 v66, v14, v66
	v_mul_f32_e32 v68, v15, v68
	v_mul_f32_e32 v66, v30, v66
	v_mul_f32_e32 v68, v31, v68
	v_cvt_pk_bf16_f32 v66, v66, v66
	v_cvt_pk_bf16_f32 v68, v68, v68
	global_store_short v67, v66, s[34:35]
	global_store_short v69, v68, s[34:35]
	v_mul_f32_e32 v66, 0xbfb8aa3b, v16
	v_mul_f32_e32 v68, 0xbfb8aa3b, v17
	v_exp_f32_e32 v66, v66
	v_exp_f32_e32 v68, v68
	v_add_u32_e32 v67, 0x23c00, v94
	v_add_f32_e32 v66, 1.0, v66
	v_add_f32_e32 v68, 1.0, v68
	v_rcp_f32_e32 v66, v66
	v_rcp_f32_e32 v68, v68
	v_add_u32_e32 v69, 0x25200, v94
	v_mul_f32_e32 v66, v16, v66
	v_mul_f32_e32 v68, v17, v68
	v_mul_f32_e32 v66, v32, v66
	v_mul_f32_e32 v68, v33, v68
	v_cvt_pk_bf16_f32 v66, v66, v66
	v_cvt_pk_bf16_f32 v68, v68, v68
	global_store_short v67, v66, s[34:35]
	global_store_short v69, v68, s[34:35]
	s_add_u32 s36, s36, 0x200
	s_cmpk_lt_u32 s36, 0x580
	s_cbranch_scc1 .Lgc1_tile
	s_branch .Lgc1_exit

; #define TIDX opaque_tid()
; template <int AI, int BI>
; DI void gemm_stage(const u16* __restrict__ A, int lda, const u16* __restrict__ B, int ldb, char* buf, int tid) {
;     ...
;     const int S = tid + NTHR * i, row = S >> 3, c = (S & 7) ^ ((row >> 1) & 7);
;     __builtin_amdgcn_global_load_lds((const unsigned*)(A + (size_t)row * lda + c * 8), (__attribute__((address_space(3))) unsigned*)(buf + S * 16), 16, 0, 0);
;   }
; #pragma unroll
;   for (int i = 0; i < 2 * BI; ++i) {
;     const int S = tid + NTHR * i, row = S >> 3, c = (S & 7) ^ ((row >> 1) & 7);
;     __builtin_amdgcn_global_load_lds((const unsigned*)(B + (size_t)row * ldb + c * 8), (__attribute__((address_space(3))) unsigned*)(buf + 16384 + S * 16), 16, 0, 0);
;   }
; }
; template <int AI, int BI>
; DI void gemm_tile(const u16* __restrict__ A, int lda, const u16* __restrict__ B, int ldb, int nk, bool swap,
;                   f32x16 (&acc)[AI][BI], char* lds) {
;   const int tid = TIDX, lane = tid & 63, wid = tid >> 6;
;   gemm_stage<AI, BI>(A, lda, B, ldb, lds, tid);
;   asm volatile("s_waitcnt vmcnt(0)" ::: "memory");
;   __syncthreads();
;   const int wa = wid >> 1, wb = wid & 1, r = lane & 31, h = lane >> 5, sw = (r >> 1) & 7;
;   const int offA = (swap ? 16384 : 0) + (wa * 32 * AI + r) * 128;
;   const int offB = (swap ? 0 : 16384) + (wb * 32 * BI + r) * 128;
.LBB0_1208:
	v_readlane_b32 s6, v244, 59
	v_readlane_b32 s10, v242, 9
	v_readlane_b32 s7, v244, 60
	v_readlane_b32 s11, v242, 10
	s_or_b64 s[6:7], s[10:11], s[6:7]
	s_and_b64 vcc, exec, s[6:7]
	s_cbranch_vccnz .LBB0_1212
	s_add_u32 s10, s8, 0x77b7000
	s_addc_u32 s11, s9, 0
	s_add_u32 s12, s8, 0x1d537000
	s_addc_u32 s13, s9, 0
	s_add_u32 s6, s8, 0x9bb7000
	s_addc_u32 s7, s9, 0
	v_readlane_b32 s14, v243, 18
	v_readlane_b32 s15, v243, 10
	v_readlane_b32 s16, v243, 8
	v_readlane_b32 s48, v243, 7
	v_readlane_b32 s49, v243, 9
	v_readlane_b32 s50, v243, 11
	s_movk_i32 s51, 0xb00
	s_mov_b32 s52, 0x1ffffe0
	s_mov_b32 s53, 0xffffe0
	s_mov_b64 s[56:57], 0x200
	s_mov_b64 s[64:65], 0x80
	s_mov_b64 s[66:67], 0x180
	s_mov_b64 s[68:69], 0x280
	s_mov_b64 s[70:71], 0x300
	s_mov_b64 s[72:73], 0x380
	s_mov_b64 s[74:75], 0x400
	s_mov_b64 s[76:77], 0x480
	s_mov_b64 s[80:81], 0x500
	s_mov_b64 s[82:83], 0x580
	s_mov_b64 s[84:85], 0x600
	s_waitcnt vmcnt(0)
	s_cmpk_lg_u32 s92, 0x200
	s_cbranch_scc1 .LBB0_1210
	v_and_b32_e32 v95, 31, v178
	v_bfe_u32 v96, v178, 5, 1
	v_bfe_u32 v97, v178, 1, 3
	v_bfe_u32 v98, v178, 7, 1
	v_lshl_add_u32 v98, v98, 5, v95
	v_lshlrev_b32_e32 v98, 7, v98
	v_add_u32_e32 v98, 0xc000, v98
	v_bfe_u32 v99, v178, 6, 1
	v_lshl_add_u32 v99, v99, 6, v95
	v_lshlrev_b32_e32 v99, 7, v99
	v_mov_b32_e32 v0, v96
	v_xor_b32_e32 v0, v0, v97
	v_lshlrev_b32_e32 v0, 4, v0
	v_add_u32_e32 v82, v98, v0
	v_add_u32_e32 v86, v99, v0
	v_add_u32_e32 v0, 2, v96
	v_xor_b32_e32 v0, v0, v97
	v_lshlrev_b32_e32 v0, 4, v0
	v_add_u32_e32 v83, v98, v0
	v_add_u32_e32 v87, v99, v0
	v_add_u32_e32 v0, 4, v96
	v_xor_b32_e32 v0, v0, v97
	v_lshlrev_b32_e32 v0, 4, v0
	v_add_u32_e32 v84, v98, v0
	v_add_u32_e32 v88, v99, v0
	v_add_u32_e32 v0, 6, v96
	v_xor_b32_e32 v0, v0, v97
	v_lshlrev_b32_e32 v0, 4, v0
	v_add_u32_e32 v85, v98, v0
	v_add_u32_e32 v89, v99, v0
	v_bfe_u32 v96, v178, 7, 1
	v_lshlrev_b32_e32 v96, 5, v96
	v_bfe_u32 v97, v178, 5, 1
	v_lshl_add_u32 v96, v97, 2, v96
	v_mul_u32_u24_e32 v96, 0xb00, v96
	v_bfe_u32 v97, v178, 6, 1
	v_lshl_add_u32 v97, v97, 5, v95
	v_add_u32_e32 v96, v96, v97
	v_lshlrev_b32_e32 v94, 1, v96
	v_lshrrev_b32_e32 v95, 3, v178
	v_and_b32_e32 v96, 7, v178
	v_bfe_u32 v97, v178, 4, 3
	v_xor_b32_e32 v96, v96, v97
	v_lshlrev_b32_e32 v96, 4, v96
	v_lshl_add_u32 v90, v95, 11, v96
	v_add_u32_e32 v91, 0x10000, v90
	v_add_u32_e32 v92, 0x20000, v90
	v_add_u32_e32 v93, 0x30000, v90
	v_lshrrev_b32_e32 v95, 6, v178
	s_nop 1
	v_readfirstlane_b32 s17, v95
	s_lshl_b32 s17, s17, 10
	s_mov_b32 s36, s14
